# prepass_sample loads batched; last-tile pool rows batched; prompt conv as 4 partial chains; P7 epilogue stores write-through (sc1); attention rebalance dropped
# speedup vs baseline: 1.0084x; 1.0047x over previous
.LBB0_1228:
	s_or_b64 exec, exec, s[30:31]
	v_lshl_add_u32 v165, s65, 10, v162
	ds_read2_b32 v[168:169], v165 offset1:16
	v_lshl_add_u32 v166, s26, 8, v159
	v_lshl_add_u32 v156, s27, 8, v161
	v_ashrrev_i32_e32 v167, 31, v166
	v_ashrrev_i32_e32 v157, 31, v156
	s_waitcnt lgkmcnt(0)
	v_pk_mul_f32 v[138:139], v[138:139], v[168:169] op_sel_hi:[1,0]
	v_pk_mul_f32 v[142:143], v[142:143], v[168:169] op_sel_hi:[1,0]
	v_pk_mul_f32 v[140:141], v[140:141], v[168:169] op_sel_hi:[1,0]
	v_max_f32_e32 v138, 0, v138
	v_lshlrev_b64 v[170:171], 13, v[166:167]
	v_pk_mul_f32 v[144:145], v[144:145], v[168:169] op_sel_hi:[1,0]
	v_mul_f32_e32 v167, v138, v138
	v_max_f32_e32 v138, 0, v143
	v_max_f32_e32 v139, 0, v139
	v_max_f32_e32 v140, 0, v140
	v_lshl_add_u64 v[170:171], s[14:15], 0, v[170:171]
	v_lshlrev_b64 v[172:173], 1, v[156:157]
	v_max_f32_e32 v142, 0, v142
	v_mul_f32_e32 v138, v138, v138
	v_mul_f32_e32 v143, v139, v139
	v_max_f32_e32 v139, 0, v144
	v_mul_f32_e32 v144, v140, v140
	v_max_f32_e32 v140, 0, v145
	v_max_f32_e32 v141, 0, v141
	v_pk_mul_f32 v[132:133], v[132:133], v[168:169] op_sel_hi:[1,0]
	v_pk_mul_f32 v[130:131], v[130:131], v[168:169] op_sel_hi:[1,0]
	v_lshl_add_u64 v[156:157], v[170:171], 0, v[172:173]
	v_mul_f32_e32 v142, v142, v142
	v_mul_f32_e32 v139, v139, v139
	v_mul_f32_e32 v140, v140, v140
	v_mul_f32_e32 v141, v141, v141
	v_cvt_pk_bf16_f32 v138, v142, v138
	v_pk_mul_f32 v[136:137], v[136:137], v[168:169] op_sel_hi:[1,0]
	v_pk_mul_f32 v[134:135], v[134:135], v[168:169] op_sel_hi:[1,0]
	v_max_f32_e32 v130, 0, v130
	v_max_f32_e32 v131, 0, v131
	v_max_f32_e32 v132, 0, v132
	v_cvt_pk_bf16_f32 v139, v139, v140
	v_cvt_pk_bf16_f32 v140, v167, v143
	v_cvt_pk_bf16_f32 v141, v144, v141
	global_store_dwordx4 v[156:157], v[138:141], off sc1
	v_max_f32_e32 v133, 0, v133
	v_max_f32_e32 v134, 0, v134
	v_mul_f32_e32 v138, v130, v130
	v_max_f32_e32 v130, 0, v135
	v_mul_f32_e32 v135, v131, v131
	v_max_f32_e32 v131, 0, v136
	v_mul_f32_e32 v136, v132, v132
	v_max_f32_e32 v132, 0, v137
	v_mul_f32_e32 v131, v131, v131
	v_mul_f32_e32 v132, v132, v132
	v_mul_f32_e32 v130, v130, v130
	v_mul_f32_e32 v133, v133, v133
	v_cvt_pk_bf16_f32 v131, v131, v132
	v_cvt_pk_bf16_f32 v132, v138, v135
	v_mul_f32_e32 v134, v134, v134
	v_cvt_pk_bf16_f32 v130, v134, v130
	v_cvt_pk_bf16_f32 v133, v136, v133
	global_store_dwordx4 v[156:157], v[130:133], off offset:256 sc1
	s_mov_b32 s19, 0x100000
	s_mov_b64 s[26:27], 0x100000
	v_mov_b32_e32 v132, v169
	v_or_b32_e32 v130, 16, v166
	v_pk_mul_f32 v[122:123], v[122:123], v[132:133] op_sel_hi:[1,0]
	v_ashrrev_i32_e32 v131, 31, v130
	v_pk_mul_f32 v[126:127], v[126:127], v[132:133] op_sel_hi:[1,0]
	v_pk_mul_f32 v[124:125], v[124:125], v[132:133] op_sel_hi:[1,0]
	v_max_f32_e32 v122, 0, v122
	v_lshlrev_b64 v[130:131], 13, v[130:131]
	v_pk_mul_f32 v[128:129], v[128:129], v[132:133] op_sel_hi:[1,0]
	v_mul_f32_e32 v133, v122, v122
	v_max_f32_e32 v122, 0, v127
	v_max_f32_e32 v123, 0, v123
	v_max_f32_e32 v124, 0, v124
	v_lshl_add_u64 v[130:131], s[14:15], 0, v[130:131]
	v_max_f32_e32 v126, 0, v126
	v_mul_f32_e32 v122, v122, v122
	v_mul_f32_e32 v127, v123, v123
	v_max_f32_e32 v123, 0, v128
	v_mul_f32_e32 v128, v124, v124
	v_max_f32_e32 v124, 0, v129
	v_max_f32_e32 v125, 0, v125
	v_pk_mul_f32 v[116:117], v[116:117], v[132:133] op_sel_hi:[1,0]
	v_pk_mul_f32 v[114:115], v[114:115], v[132:133] op_sel_hi:[1,0]
	v_lshl_add_u64 v[130:131], v[130:131], 0, v[172:173]
	v_mul_f32_e32 v126, v126, v126
	v_mul_f32_e32 v123, v123, v123
	v_mul_f32_e32 v124, v124, v124
	v_mul_f32_e32 v125, v125, v125
	v_cvt_pk_bf16_f32 v122, v126, v122
	v_pk_mul_f32 v[120:121], v[120:121], v[132:133] op_sel_hi:[1,0]
	v_pk_mul_f32 v[118:119], v[118:119], v[132:133] op_sel_hi:[1,0]
	v_max_f32_e32 v114, 0, v114
	v_max_f32_e32 v115, 0, v115
	v_max_f32_e32 v116, 0, v116
	v_cvt_pk_bf16_f32 v123, v123, v124
	v_cvt_pk_bf16_f32 v124, v133, v127
	v_cvt_pk_bf16_f32 v125, v128, v125
	global_store_dwordx4 v[130:131], v[122:125], off sc1
	v_max_f32_e32 v117, 0, v117
	v_mul_f32_e32 v117, v117, v117
	v_mul_f32_e32 v122, v114, v114
	v_max_f32_e32 v114, 0, v119
	v_mul_f32_e32 v119, v115, v115
	v_max_f32_e32 v115, 0, v120
	v_mul_f32_e32 v120, v116, v116
	v_max_f32_e32 v116, 0, v121
	v_mul_f32_e32 v115, v115, v115
	v_mul_f32_e32 v116, v116, v116
	v_max_f32_e32 v118, 0, v118
	v_mul_f32_e32 v114, v114, v114
	v_cvt_pk_bf16_f32 v115, v115, v116
	v_cvt_pk_bf16_f32 v116, v122, v119
	v_cvt_pk_bf16_f32 v117, v120, v117
	v_mul_f32_e32 v118, v118, v118
	v_cvt_pk_bf16_f32 v114, v118, v114
	global_store_dwordx4 v[130:131], v[114:117], off offset:256 sc1
	ds_read2_b32 v[116:117], v165 offset0:32 offset1:48
	s_waitcnt lgkmcnt(0)
	v_pk_mul_f32 v[106:107], v[106:107], v[116:117] op_sel_hi:[1,0]
	v_or_b32_e32 v114, 32, v166
	v_ashrrev_i32_e32 v115, 31, v114
	v_pk_mul_f32 v[110:111], v[110:111], v[116:117] op_sel_hi:[1,0]
	v_pk_mul_f32 v[108:109], v[108:109], v[116:117] op_sel_hi:[1,0]
	v_max_f32_e32 v106, 0, v106
	v_lshlrev_b64 v[114:115], 13, v[114:115]
	v_pk_mul_f32 v[112:113], v[112:113], v[116:117] op_sel_hi:[1,0]
	v_mul_f32_e32 v118, v106, v106
	v_max_f32_e32 v106, 0, v111
	v_max_f32_e32 v107, 0, v107
	v_max_f32_e32 v108, 0, v108
	v_lshl_add_u64 v[114:115], s[14:15], 0, v[114:115]
	v_max_f32_e32 v110, 0, v110
	v_mul_f32_e32 v106, v106, v106
	v_mul_f32_e32 v111, v107, v107
	v_max_f32_e32 v107, 0, v112
	v_mul_f32_e32 v112, v108, v108
	v_max_f32_e32 v108, 0, v113
	v_max_f32_e32 v109, 0, v109
	v_pk_mul_f32 v[100:101], v[100:101], v[116:117] op_sel_hi:[1,0]
	v_pk_mul_f32 v[98:99], v[98:99], v[116:117] op_sel_hi:[1,0]
	v_lshl_add_u64 v[114:115], v[114:115], 0, v[172:173]
	v_mul_f32_e32 v110, v110, v110
	v_mul_f32_e32 v107, v107, v107
	v_mul_f32_e32 v108, v108, v108
	v_mul_f32_e32 v109, v109, v109
	v_cvt_pk_bf16_f32 v106, v110, v106
	v_pk_mul_f32 v[104:105], v[104:105], v[116:117] op_sel_hi:[1,0]
	v_pk_mul_f32 v[102:103], v[102:103], v[116:117] op_sel_hi:[1,0]
	v_max_f32_e32 v98, 0, v98
	v_max_f32_e32 v99, 0, v99
	v_max_f32_e32 v100, 0, v100
	v_cvt_pk_bf16_f32 v107, v107, v108
	v_cvt_pk_bf16_f32 v108, v118, v111
	v_cvt_pk_bf16_f32 v109, v112, v109
	global_store_dwordx4 v[114:115], v[106:109], off sc1
	v_max_f32_e32 v101, 0, v101
	v_max_f32_e32 v102, 0, v102
	v_mul_f32_e32 v106, v98, v98
	v_max_f32_e32 v98, 0, v103
	v_mul_f32_e32 v103, v99, v99
	v_max_f32_e32 v99, 0, v104
	v_mul_f32_e32 v104, v100, v100
	v_max_f32_e32 v100, 0, v105
	v_mul_f32_e32 v99, v99, v99
	v_mul_f32_e32 v100, v100, v100
	v_mul_f32_e32 v98, v98, v98
	v_mul_f32_e32 v101, v101, v101
	v_cvt_pk_bf16_f32 v99, v99, v100
	v_cvt_pk_bf16_f32 v100, v106, v103
	v_mul_f32_e32 v102, v102, v102
	v_cvt_pk_bf16_f32 v98, v102, v98
	v_cvt_pk_bf16_f32 v101, v104, v101
	global_store_dwordx4 v[114:115], v[98:101], off offset:256 sc1
	s_nop 1
	v_mov_b32_e32 v100, v117
	v_or_b32_e32 v98, 48, v166
	v_pk_mul_f32 v[90:91], v[90:91], v[100:101] op_sel_hi:[1,0]
	v_ashrrev_i32_e32 v99, 31, v98
	v_pk_mul_f32 v[94:95], v[94:95], v[100:101] op_sel_hi:[1,0]
	v_pk_mul_f32 v[92:93], v[92:93], v[100:101] op_sel_hi:[1,0]
	v_max_f32_e32 v90, 0, v90
	v_lshlrev_b64 v[98:99], 13, v[98:99]
	v_pk_mul_f32 v[96:97], v[96:97], v[100:101] op_sel_hi:[1,0]
	v_mul_f32_e32 v101, v90, v90
	v_max_f32_e32 v90, 0, v95
	v_max_f32_e32 v91, 0, v91
	v_max_f32_e32 v92, 0, v92
	v_lshl_add_u64 v[98:99], s[14:15], 0, v[98:99]
	v_max_f32_e32 v94, 0, v94
	v_mul_f32_e32 v90, v90, v90
	v_mul_f32_e32 v95, v91, v91
	v_max_f32_e32 v91, 0, v96
	v_mul_f32_e32 v96, v92, v92
	v_max_f32_e32 v92, 0, v97
	v_max_f32_e32 v93, 0, v93
	v_pk_mul_f32 v[82:83], v[82:83], v[100:101] op_sel_hi:[1,0]
	v_lshl_add_u64 v[98:99], v[98:99], 0, v[172:173]
	v_mul_f32_e32 v94, v94, v94
	v_mul_f32_e32 v91, v91, v91
	v_mul_f32_e32 v92, v92, v92
	v_mul_f32_e32 v93, v93, v93
	v_cvt_pk_bf16_f32 v90, v94, v90
	v_pk_mul_f32 v[86:87], v[86:87], v[100:101] op_sel_hi:[1,0]
	v_max_f32_e32 v82, 0, v82
	v_cvt_pk_bf16_f32 v91, v91, v92
	v_cvt_pk_bf16_f32 v92, v101, v95
	v_cvt_pk_bf16_f32 v93, v96, v93
	global_store_dwordx4 v[98:99], v[90:93], off sc1
	v_max_f32_e32 v86, 0, v86
	v_mul_f32_e32 v86, v86, v86
	v_mul_f32_e32 v90, v82, v82
	v_max_f32_e32 v82, 0, v87
	v_mul_f32_e32 v82, v82, v82
	v_cvt_pk_bf16_f32 v82, v86, v82
	ds_read2_b32 v[86:87], v165 offset0:128 offset1:144
	v_pk_mul_f32 v[84:85], v[84:85], v[100:101] op_sel_hi:[1,0]
	v_pk_mul_f32 v[88:89], v[88:89], v[100:101] op_sel_hi:[1,0]
	v_max_f32_e32 v83, 0, v83
	v_max_f32_e32 v84, 0, v84
	v_mul_f32_e32 v91, v83, v83
	v_max_f32_e32 v83, 0, v88
	v_mul_f32_e32 v88, v84, v84
	v_max_f32_e32 v84, 0, v89
	v_mul_f32_e32 v83, v83, v83
	v_max_f32_e32 v85, 0, v85
	v_mul_f32_e32 v84, v84, v84
	s_waitcnt lgkmcnt(0)
	v_pk_mul_f32 v[74:75], v[74:75], v[86:87] op_sel_hi:[1,0]
	v_mul_f32_e32 v85, v85, v85
	v_cvt_pk_bf16_f32 v83, v83, v84
	v_cvt_pk_bf16_f32 v84, v90, v91
	v_pk_mul_f32 v[78:79], v[78:79], v[86:87] op_sel_hi:[1,0]
	v_pk_mul_f32 v[76:77], v[76:77], v[86:87] op_sel_hi:[1,0]
	v_max_f32_e32 v74, 0, v74
	v_cvt_pk_bf16_f32 v85, v88, v85
	global_store_dwordx4 v[98:99], v[82:85], off offset:256 sc1
	v_pk_mul_f32 v[80:81], v[80:81], v[86:87] op_sel_hi:[1,0]
	v_max_f32_e32 v78, 0, v78
	v_mul_f32_e32 v84, v74, v74
	v_max_f32_e32 v74, 0, v79
	v_max_f32_e32 v75, 0, v75
	v_max_f32_e32 v76, 0, v76
	v_mul_f32_e32 v78, v78, v78
	v_mul_f32_e32 v74, v74, v74
	v_mul_f32_e32 v79, v75, v75
	v_max_f32_e32 v75, 0, v80
	v_mul_f32_e32 v80, v76, v76
	v_max_f32_e32 v76, 0, v81
	v_mul_f32_e32 v75, v75, v75
	v_max_f32_e32 v77, 0, v77
	v_mul_f32_e32 v76, v76, v76
	v_cvt_pk_bf16_f32 v74, v78, v74
	v_add_co_u32_e32 v78, vcc, s19, v156
	v_pk_mul_f32 v[68:69], v[68:69], v[86:87] op_sel_hi:[1,0]
	v_pk_mul_f32 v[66:67], v[66:67], v[86:87] op_sel_hi:[1,0]
	v_mul_f32_e32 v77, v77, v77
	v_cvt_pk_bf16_f32 v75, v75, v76
	v_cvt_pk_bf16_f32 v76, v84, v79
	v_addc_co_u32_e32 v79, vcc, 0, v157, vcc
	v_pk_mul_f32 v[72:73], v[72:73], v[86:87] op_sel_hi:[1,0]
	v_pk_mul_f32 v[70:71], v[70:71], v[86:87] op_sel_hi:[1,0]
	v_max_f32_e32 v66, 0, v66
	v_max_f32_e32 v67, 0, v67
	v_max_f32_e32 v68, 0, v68
	v_cvt_pk_bf16_f32 v77, v80, v77
	global_store_dwordx4 v[78:79], v[74:77], off sc1
	v_max_f32_e32 v69, 0, v69
	v_lshl_add_u64 v[82:83], v[156:157], 0, s[26:27]
	v_mul_f32_e32 v74, v66, v66
	v_max_f32_e32 v66, 0, v71
	v_mul_f32_e32 v71, v67, v67
	v_max_f32_e32 v67, 0, v72
	v_mul_f32_e32 v72, v68, v68
	v_max_f32_e32 v68, 0, v73
	v_mul_f32_e32 v67, v67, v67
	v_mul_f32_e32 v68, v68, v68
	v_max_f32_e32 v70, 0, v70
	v_mul_f32_e32 v66, v66, v66
	v_mul_f32_e32 v69, v69, v69
	v_cvt_pk_bf16_f32 v67, v67, v68
	v_cvt_pk_bf16_f32 v68, v74, v71
	v_mul_f32_e32 v70, v70, v70
	v_cvt_pk_bf16_f32 v66, v70, v66
	v_cvt_pk_bf16_f32 v69, v72, v69
	global_store_dwordx4 v[82:83], v[66:69], off offset:256 sc1
	s_mov_b32 s19, 0x120000
	s_mov_b64 s[26:27], 0x120000
	v_mov_b32_e32 v68, v87
	v_pk_mul_f32 v[58:59], v[58:59], v[68:69] op_sel_hi:[1,0]
	v_pk_mul_f32 v[62:63], v[62:63], v[68:69] op_sel_hi:[1,0]
	v_pk_mul_f32 v[60:61], v[60:61], v[68:69] op_sel_hi:[1,0]
	v_max_f32_e32 v58, 0, v58
	v_pk_mul_f32 v[64:65], v[64:65], v[68:69] op_sel_hi:[1,0]
	v_max_f32_e32 v62, 0, v62
	v_mul_f32_e32 v69, v58, v58
	v_max_f32_e32 v58, 0, v63
	v_max_f32_e32 v59, 0, v59
	v_max_f32_e32 v60, 0, v60
	v_mul_f32_e32 v62, v62, v62
	v_mul_f32_e32 v58, v58, v58
	v_mul_f32_e32 v63, v59, v59
	v_max_f32_e32 v59, 0, v64
	v_mul_f32_e32 v64, v60, v60
	v_max_f32_e32 v60, 0, v65
	v_mul_f32_e32 v59, v59, v59
	v_max_f32_e32 v61, 0, v61
	v_mul_f32_e32 v60, v60, v60
	v_cvt_pk_bf16_f32 v58, v62, v58
	v_add_co_u32_e32 v62, vcc, s19, v156
	v_pk_mul_f32 v[50:51], v[50:51], v[68:69] op_sel_hi:[1,0]
	v_mul_f32_e32 v61, v61, v61
	v_cvt_pk_bf16_f32 v59, v59, v60
	v_cvt_pk_bf16_f32 v60, v69, v63
	v_addc_co_u32_e32 v63, vcc, 0, v157, vcc
	v_pk_mul_f32 v[54:55], v[54:55], v[68:69] op_sel_hi:[1,0]
	v_max_f32_e32 v50, 0, v50
	v_cvt_pk_bf16_f32 v61, v64, v61
	global_store_dwordx4 v[62:63], v[58:61], off sc1
	v_max_f32_e32 v54, 0, v54
	v_mul_f32_e32 v54, v54, v54
	v_mul_f32_e32 v58, v50, v50
	v_max_f32_e32 v50, 0, v55
	v_mul_f32_e32 v50, v50, v50
	v_cvt_pk_bf16_f32 v50, v54, v50
	ds_read2_b32 v[54:55], v165 offset0:160 offset1:176
	v_pk_mul_f32 v[52:53], v[52:53], v[68:69] op_sel_hi:[1,0]
	v_pk_mul_f32 v[56:57], v[56:57], v[68:69] op_sel_hi:[1,0]
	v_max_f32_e32 v51, 0, v51
	v_max_f32_e32 v52, 0, v52
	v_mul_f32_e32 v59, v51, v51
	v_max_f32_e32 v51, 0, v56
	v_mul_f32_e32 v56, v52, v52
	v_max_f32_e32 v52, 0, v57
	v_mul_f32_e32 v51, v51, v51
	v_max_f32_e32 v53, 0, v53
	v_mul_f32_e32 v52, v52, v52
	s_waitcnt lgkmcnt(0)
	v_pk_mul_f32 v[42:43], v[42:43], v[54:55] op_sel_hi:[1,0]
	v_lshl_add_u64 v[66:67], v[156:157], 0, s[26:27]
	v_mul_f32_e32 v53, v53, v53
	v_cvt_pk_bf16_f32 v51, v51, v52
	v_cvt_pk_bf16_f32 v52, v58, v59
	v_pk_mul_f32 v[46:47], v[46:47], v[54:55] op_sel_hi:[1,0]
	v_pk_mul_f32 v[44:45], v[44:45], v[54:55] op_sel_hi:[1,0]
	v_max_f32_e32 v42, 0, v42
	v_cvt_pk_bf16_f32 v53, v56, v53
	global_store_dwordx4 v[66:67], v[50:53], off offset:256 sc1
	v_pk_mul_f32 v[48:49], v[48:49], v[54:55] op_sel_hi:[1,0]
	v_max_f32_e32 v46, 0, v46
	v_mul_f32_e32 v52, v42, v42
	v_max_f32_e32 v42, 0, v47
	v_max_f32_e32 v43, 0, v43
	v_max_f32_e32 v44, 0, v44
	v_mul_f32_e32 v46, v46, v46
	v_mul_f32_e32 v42, v42, v42
	v_mul_f32_e32 v47, v43, v43
	v_max_f32_e32 v43, 0, v48
	v_mul_f32_e32 v48, v44, v44
	v_max_f32_e32 v44, 0, v49
	s_mov_b32 s19, 0x140000
	v_mul_f32_e32 v43, v43, v43
	v_max_f32_e32 v45, 0, v45
	v_mul_f32_e32 v44, v44, v44
	v_cvt_pk_bf16_f32 v42, v46, v42
	v_add_co_u32_e32 v46, vcc, s19, v156
	v_pk_mul_f32 v[36:37], v[36:37], v[54:55] op_sel_hi:[1,0]
	v_pk_mul_f32 v[34:35], v[34:35], v[54:55] op_sel_hi:[1,0]
	v_mul_f32_e32 v45, v45, v45
	v_cvt_pk_bf16_f32 v43, v43, v44
	v_cvt_pk_bf16_f32 v44, v52, v47
	v_addc_co_u32_e32 v47, vcc, 0, v157, vcc
	v_pk_mul_f32 v[40:41], v[40:41], v[54:55] op_sel_hi:[1,0]
	v_pk_mul_f32 v[38:39], v[38:39], v[54:55] op_sel_hi:[1,0]
	v_max_f32_e32 v34, 0, v34
	v_max_f32_e32 v35, 0, v35
	v_max_f32_e32 v36, 0, v36
	v_cvt_pk_bf16_f32 v45, v48, v45
	global_store_dwordx4 v[46:47], v[42:45], off sc1
	s_mov_b64 s[26:27], 0x140000
	v_max_f32_e32 v37, 0, v37
	v_mul_f32_e32 v42, v34, v34
	v_max_f32_e32 v34, 0, v39
	v_mul_f32_e32 v39, v35, v35
	v_max_f32_e32 v35, 0, v40
	v_mul_f32_e32 v40, v36, v36
	v_max_f32_e32 v36, 0, v41
	v_mul_f32_e32 v35, v35, v35
	v_mul_f32_e32 v36, v36, v36
	v_lshl_add_u64 v[50:51], v[156:157], 0, s[26:27]
	v_max_f32_e32 v38, 0, v38
	v_mul_f32_e32 v34, v34, v34
	v_mul_f32_e32 v37, v37, v37
	v_cvt_pk_bf16_f32 v35, v35, v36
	v_cvt_pk_bf16_f32 v36, v42, v39
	v_mul_f32_e32 v38, v38, v38
	v_cvt_pk_bf16_f32 v34, v38, v34
	v_cvt_pk_bf16_f32 v37, v40, v37
	global_store_dwordx4 v[50:51], v[34:37], off offset:256 sc1
	s_mov_b32 s19, 0x160000
	s_mov_b64 s[26:27], 0x160000
	v_mov_b32_e32 v36, v55
	v_pk_mul_f32 v[26:27], v[26:27], v[36:37] op_sel_hi:[1,0]
	v_pk_mul_f32 v[30:31], v[30:31], v[36:37] op_sel_hi:[1,0]
	v_pk_mul_f32 v[28:29], v[28:29], v[36:37] op_sel_hi:[1,0]
	v_max_f32_e32 v26, 0, v26
	v_pk_mul_f32 v[32:33], v[32:33], v[36:37] op_sel_hi:[1,0]
	v_max_f32_e32 v30, 0, v30
	v_mul_f32_e32 v37, v26, v26
	v_max_f32_e32 v26, 0, v31
	v_max_f32_e32 v27, 0, v27
	v_max_f32_e32 v28, 0, v28
	v_mul_f32_e32 v30, v30, v30
	v_mul_f32_e32 v26, v26, v26
	v_mul_f32_e32 v31, v27, v27
	v_max_f32_e32 v27, 0, v32
	v_mul_f32_e32 v32, v28, v28
	v_max_f32_e32 v28, 0, v33
	v_mul_f32_e32 v27, v27, v27
	v_max_f32_e32 v29, 0, v29
	v_mul_f32_e32 v28, v28, v28
	v_cvt_pk_bf16_f32 v26, v30, v26
	v_add_co_u32_e32 v30, vcc, s19, v156
	v_pk_mul_f32 v[20:21], v[20:21], v[36:37] op_sel_hi:[1,0]
	v_pk_mul_f32 v[18:19], v[18:19], v[36:37] op_sel_hi:[1,0]
	v_mul_f32_e32 v29, v29, v29
	v_cvt_pk_bf16_f32 v27, v27, v28
	v_cvt_pk_bf16_f32 v28, v37, v31
	v_addc_co_u32_e32 v31, vcc, 0, v157, vcc
	v_pk_mul_f32 v[24:25], v[24:25], v[36:37] op_sel_hi:[1,0]
	v_pk_mul_f32 v[22:23], v[22:23], v[36:37] op_sel_hi:[1,0]
	v_max_f32_e32 v18, 0, v18
	v_max_f32_e32 v19, 0, v19
	v_max_f32_e32 v20, 0, v20
	v_cvt_pk_bf16_f32 v29, v32, v29
	global_store_dwordx4 v[30:31], v[26:29], off sc1
	v_max_f32_e32 v21, 0, v21
	v_lshl_add_u64 v[34:35], v[156:157], 0, s[26:27]
	v_mul_f32_e32 v26, v18, v18
	v_max_f32_e32 v18, 0, v23
	v_mul_f32_e32 v23, v19, v19
	v_max_f32_e32 v19, 0, v24
	v_mul_f32_e32 v24, v20, v20
	v_max_f32_e32 v20, 0, v25
	v_max_f32_e32 v22, 0, v22
	v_mul_f32_e32 v18, v18, v18
	v_mul_f32_e32 v19, v19, v19
	v_mul_f32_e32 v20, v20, v20
	v_mul_f32_e32 v21, v21, v21
	v_mul_f32_e32 v22, v22, v22
	v_cvt_pk_bf16_f32 v18, v22, v18
	v_cvt_pk_bf16_f32 v19, v19, v20
	v_cvt_pk_bf16_f32 v20, v26, v23
	v_cvt_pk_bf16_f32 v21, v24, v21
	global_store_dwordx4 v[34:35], v[18:21], off offset:256 sc1
	s_and_saveexec_b64 s[26:27], s[28:29]
	s_cbranch_execz .LBB0_1230
	s_waitcnt vmcnt(0)
	v_mov_b32_e32 v18, v3
	v_mov_b32_e32 v19, v4
	v_mov_b32_e32 v20, v2
	v_mov_b32_e32 v21, v5
	v_pk_add_f32 v[18:19], v[18:19], v[20:21]
	v_mov_b32_e32 v20, v7
	v_mov_b32_e32 v21, v8
	v_mov_b32_e32 v22, v6
	v_mov_b32_e32 v23, v9
	v_pk_add_f32 v[20:21], v[20:21], v[22:23]
	v_pk_add_f32 v[18:19], v[18:19], v[18:19] op_sel:[0,1] op_sel_hi:[1,0]
	v_pk_add_f32 v[20:21], v[20:21], v[20:21] op_sel:[0,1] op_sel_hi:[1,0]
	v_add_f32_e32 v22, v10, v11
	v_add_f32_e32 v24, v12, v13
	v_mov_b32_e32 v19, v14
	v_mov_b32_e32 v21, v15
	v_mov_b32_e32 v23, v16
	v_mov_b32_e32 v25, v17
	v_pk_add_f32 v[18:19], v[18:19], v[20:21]
	v_pk_add_f32 v[20:21], v[22:23], v[24:25]
	s_lshl_b32 s19, s65, 10
	v_pk_add_f32 v[18:19], v[18:19], v[20:21]
	s_xor_b32 s19, s19, 0x400
	v_add_f32_e32 v18, v18, v19
	v_fmamk_f32 v18, v18, 0x3a800000, v234
	v_mul_f32_e32 v19, 0x4b800000, v18
	v_cmp_gt_f32_e32 vcc, s33, v18
	s_nop 1
	v_cndmask_b32_e32 v18, v18, v19, vcc
	v_rsq_f32_e32 v18, v18
	s_nop 0
	v_mul_f32_e32 v19, 0x45800000, v18
	v_cndmask_b32_e32 v18, v18, v19, vcc
	v_add_u32_e32 v19, s19, v163
	ds_write_b32 v19, v18
